# v041_poolstage
# baseline (speedup 1.0000x reference)
; __device__ __forceinline__ void pool_block_item(const Params& p, int layer, int tt, const int tidx) {
;     ...
;     u32x4 xv[12];
; #pragma unroll
;     for (int i = 0; i < 12; ++i) {
;       int c = i * NTHR + tidx;
;       if (c < 4 * PROWS * 32) {
;         int g = c / (PROWS * 32), rem = c % (PROWS * 32), r = rem >> 5, c16 = rem & 31;
;         int back = 15 - r;
;         const bool pre = back > pos0;
;         if (pre) back = pos0;
;         xv[i] = *reinterpret_cast<const u32x4*>(proj + (size_t)(t0 - back) * DIN + OFF_PX + g * 256 + c16 * 8);
;         if (pre) xv[i] = u32x4{0u, 0u, 0u, 0u};
;       }
;     }
.LBB0_124:
	s_andn2_b64 vcc, exec, s[6:7]
	s_cbranch_vccnz .LBB0_196
	s_lshl_b32 s6, s64, 5
	s_add_i32 s34, s6, 0xfffff000
	s_and_b32 s35, s6, 0xfe0
	s_movk_i32 s6, 0x1780
	v_cmp_gt_i32_e32 vcc, s6, v164
	s_mov_b32 s6, 0xae4c415d
	v_mul_hi_i32 v0, v164, s6
	v_add_u32_e32 v48, v0, v164
	s_and_saveexec_b64 s[8:9], vcc
	s_cbranch_execz .LBB0_127
	v_lshrrev_b32_e32 v0, 31, v48
	v_ashrrev_i32_e32 v1, 10, v48
	v_add_u32_e32 v2, v1, v0
	v_mul_i32_i24_e32 v0, 0x5e0, v2
	v_sub_u32_e32 v4, v164, v0
	v_ashrrev_i32_e32 v0, 5, v4
	v_sub_u32_e32 v5, 15, v0
	v_min_i32_e32 v0, s35, v5
	v_sub_u32_e32 v0, s34, v0
	s_movk_i32 s6, 0x3000
	v_mul_lo_u32 v0, v0, s6
	v_ashrrev_i32_e32 v1, 31, v0
	v_lshlrev_b32_e32 v2, 8, v2
	v_lshl_add_u64 v[0:1], v[0:1], 1, s[74:75]
	v_ashrrev_i32_e32 v3, 31, v2
	v_lshl_add_u64 v[0:1], v[2:3], 1, v[0:1]
	v_lshlrev_b32_e32 v2, 4, v4
	v_and_b32_e32 v162, 0x1f0, v2
	v_lshl_add_u64 v[0:1], v[0:1], 0, v[162:163]
	global_load_dwordx4 v[0:3], v[0:1], off
	v_cmp_ge_i32_e64 s[6:7], s35, v5
	s_nop 1
	v_cndmask_b32_e64 v100, 0, 1, s[6:7]
.LBB0_127:
	s_or_b64 exec, exec, s[8:9]
	v_add_u32_e32 v49, 0x200, v164
	s_mov_b32 s8, 0xae4c415d
	s_movk_i32 s6, 0x1580
	v_mul_hi_i32 v4, v49, s8
	v_cmp_gt_i32_e64 s[6:7], s6, v164
	v_add_u32_e32 v50, v4, v49
	s_and_saveexec_b64 s[10:11], s[6:7]
	s_cbranch_execz .LBB0_129
	v_lshrrev_b32_e32 v4, 31, v50
	v_ashrrev_i32_e32 v5, 10, v50
	v_add_u32_e32 v6, v5, v4
	v_mul_i32_i24_e32 v4, 0x5e0, v6
	v_sub_u32_e32 v8, v49, v4
	v_ashrrev_i32_e32 v4, 5, v8
	v_sub_u32_e32 v9, 15, v4
	v_min_i32_e32 v4, s35, v9
	v_sub_u32_e32 v4, s34, v4
	s_movk_i32 s8, 0x3000
	v_mul_lo_u32 v4, v4, s8
	v_ashrrev_i32_e32 v5, 31, v4
	v_lshlrev_b32_e32 v6, 8, v6
	v_lshl_add_u64 v[4:5], v[4:5], 1, s[74:75]
	v_ashrrev_i32_e32 v7, 31, v6
	v_lshl_add_u64 v[4:5], v[6:7], 1, v[4:5]
	v_lshlrev_b32_e32 v6, 4, v8
	v_and_b32_e32 v162, 0x1f0, v6
	v_lshl_add_u64 v[4:5], v[4:5], 0, v[162:163]
	global_load_dwordx4 v[4:7], v[4:5], off
	v_cmp_ge_i32_e64 s[8:9], s35, v9
	s_nop 1
	v_cndmask_b32_e64 v101, 0, 1, s[8:9]
.LBB0_129:
	s_or_b64 exec, exec, s[10:11]
	v_add_u32_e32 v51, 0x400, v164
	s_mov_b32 s10, 0xae4c415d
	s_movk_i32 s8, 0x1380
	v_mul_hi_i32 v8, v51, s10
	v_cmp_gt_i32_e64 s[8:9], s8, v164
	v_add_u32_e32 v52, v8, v51
	s_and_saveexec_b64 s[12:13], s[8:9]
	s_cbranch_execz .LBB0_131
	v_lshrrev_b32_e32 v8, 31, v52
	v_ashrrev_i32_e32 v9, 10, v52
	v_add_u32_e32 v10, v9, v8
	v_mul_i32_i24_e32 v8, 0x5e0, v10
	v_sub_u32_e32 v12, v51, v8
	v_ashrrev_i32_e32 v8, 5, v12
	v_sub_u32_e32 v13, 15, v8
	v_min_i32_e32 v8, s35, v13
	v_sub_u32_e32 v8, s34, v8
	s_movk_i32 s10, 0x3000
	v_mul_lo_u32 v8, v8, s10
	v_ashrrev_i32_e32 v9, 31, v8
	v_lshlrev_b32_e32 v10, 8, v10
	v_lshl_add_u64 v[8:9], v[8:9], 1, s[74:75]
	v_ashrrev_i32_e32 v11, 31, v10
	v_lshl_add_u64 v[8:9], v[10:11], 1, v[8:9]
	v_lshlrev_b32_e32 v10, 4, v12
	v_and_b32_e32 v162, 0x1f0, v10
	v_lshl_add_u64 v[8:9], v[8:9], 0, v[162:163]
	global_load_dwordx4 v[8:11], v[8:9], off
	v_cmp_ge_i32_e64 s[10:11], s35, v13
	s_nop 1
	v_cndmask_b32_e64 v102, 0, 1, s[10:11]
.LBB0_131:
	s_or_b64 exec, exec, s[12:13]
	v_add_u32_e32 v53, 0x600, v164
	s_mov_b32 s12, 0xae4c415d
	s_movk_i32 s10, 0x1180
	v_mul_hi_i32 v12, v53, s12
	v_cmp_gt_i32_e64 s[10:11], s10, v164
	v_add_u32_e32 v54, v12, v53
	s_and_saveexec_b64 s[14:15], s[10:11]
	s_cbranch_execz .LBB0_133
	v_lshrrev_b32_e32 v12, 31, v54
	v_ashrrev_i32_e32 v13, 10, v54
	v_add_u32_e32 v14, v13, v12
	v_mul_i32_i24_e32 v12, 0x5e0, v14
	v_sub_u32_e32 v16, v53, v12
	v_ashrrev_i32_e32 v12, 5, v16
	v_sub_u32_e32 v17, 15, v12
	v_min_i32_e32 v12, s35, v17
	v_sub_u32_e32 v12, s34, v12
	s_movk_i32 s12, 0x3000
	v_mul_lo_u32 v12, v12, s12
	v_ashrrev_i32_e32 v13, 31, v12
	v_lshlrev_b32_e32 v14, 8, v14
	v_lshl_add_u64 v[12:13], v[12:13], 1, s[74:75]
	v_ashrrev_i32_e32 v15, 31, v14
	v_lshl_add_u64 v[12:13], v[14:15], 1, v[12:13]
	v_lshlrev_b32_e32 v14, 4, v16
	v_and_b32_e32 v162, 0x1f0, v14
	v_lshl_add_u64 v[12:13], v[12:13], 0, v[162:163]
	global_load_dwordx4 v[12:15], v[12:13], off
	v_cmp_ge_i32_e64 s[12:13], s35, v17
	s_nop 1
	v_cndmask_b32_e64 v103, 0, 1, s[12:13]
.LBB0_133:
	s_or_b64 exec, exec, s[14:15]
	v_add_u32_e32 v55, 0x800, v164
	s_mov_b32 s14, 0xae4c415d
	s_movk_i32 s12, 0xf80
	v_mul_hi_i32 v16, v55, s14
	v_cmp_gt_i32_e64 s[12:13], s12, v164
	v_add_u32_e32 v56, v16, v55
	s_and_saveexec_b64 s[16:17], s[12:13]
	s_cbranch_execz .LBB0_135
	v_lshrrev_b32_e32 v16, 31, v56
	v_ashrrev_i32_e32 v17, 10, v56
	v_add_u32_e32 v18, v17, v16
	v_mul_i32_i24_e32 v16, 0x5e0, v18
	v_sub_u32_e32 v20, v55, v16
	v_ashrrev_i32_e32 v16, 5, v20
	v_sub_u32_e32 v21, 15, v16
	v_min_i32_e32 v16, s35, v21
	v_sub_u32_e32 v16, s34, v16
	s_movk_i32 s14, 0x3000
	v_mul_lo_u32 v16, v16, s14
	v_ashrrev_i32_e32 v17, 31, v16
	v_lshlrev_b32_e32 v18, 8, v18
	v_lshl_add_u64 v[16:17], v[16:17], 1, s[74:75]
	v_ashrrev_i32_e32 v19, 31, v18
	v_lshl_add_u64 v[16:17], v[18:19], 1, v[16:17]
	v_lshlrev_b32_e32 v18, 4, v20
	v_and_b32_e32 v162, 0x1f0, v18
	v_lshl_add_u64 v[16:17], v[16:17], 0, v[162:163]
	global_load_dwordx4 v[16:19], v[16:17], off
	v_cmp_ge_i32_e64 s[14:15], s35, v21
	s_nop 1
	v_cndmask_b32_e64 v104, 0, 1, s[14:15]
; __device__ __forceinline__ void pool_block_item(const Params& p, int layer, int tt, const int tidx) {
;     ...
;     u32x4 xv[12];
; #pragma unroll
;     for (int i = 0; i < 12; ++i) {
;       int c = i * NTHR + tidx;
;       if (c < 4 * PROWS * 32) {
;         int g = c / (PROWS * 32), rem = c % (PROWS * 32), r = rem >> 5, c16 = rem & 31;
;         int back = 15 - r;
;         const bool pre = back > pos0;
;         if (pre) back = pos0;
;         xv[i] = *reinterpret_cast<const u32x4*>(proj + (size_t)(t0 - back) * DIN + OFF_PX + g * 256 + c16 * 8);
;         if (pre) xv[i] = u32x4{0u, 0u, 0u, 0u};
;       }
;     }
.LBB0_135:
	s_or_b64 exec, exec, s[16:17]
	v_add_u32_e32 v57, 0xa00, v164
	s_mov_b32 s16, 0xae4c415d
	s_movk_i32 s14, 0xd80
	v_mul_hi_i32 v20, v57, s16
	v_cmp_gt_i32_e64 s[14:15], s14, v164
	v_add_u32_e32 v58, v20, v57
	s_and_saveexec_b64 s[18:19], s[14:15]
	s_cbranch_execz .LBB0_137
	v_lshrrev_b32_e32 v20, 31, v58
	v_ashrrev_i32_e32 v21, 10, v58
	v_add_u32_e32 v22, v21, v20
	v_mul_i32_i24_e32 v20, 0x5e0, v22
	v_sub_u32_e32 v24, v57, v20
	v_ashrrev_i32_e32 v20, 5, v24
	v_sub_u32_e32 v25, 15, v20
	v_min_i32_e32 v20, s35, v25
	v_sub_u32_e32 v20, s34, v20
	s_movk_i32 s16, 0x3000
	v_mul_lo_u32 v20, v20, s16
	v_ashrrev_i32_e32 v21, 31, v20
	v_lshlrev_b32_e32 v22, 8, v22
	v_lshl_add_u64 v[20:21], v[20:21], 1, s[74:75]
	v_ashrrev_i32_e32 v23, 31, v22
	v_lshl_add_u64 v[20:21], v[22:23], 1, v[20:21]
	v_lshlrev_b32_e32 v22, 4, v24
	v_and_b32_e32 v162, 0x1f0, v22
	v_lshl_add_u64 v[20:21], v[20:21], 0, v[162:163]
	global_load_dwordx4 v[20:23], v[20:21], off
	v_cmp_ge_i32_e64 s[16:17], s35, v25
	s_nop 1
	v_cndmask_b32_e64 v105, 0, 1, s[16:17]
.LBB0_137:
	s_or_b64 exec, exec, s[18:19]
	v_add_u32_e32 v59, 0xc00, v164
	s_mov_b32 s18, 0xae4c415d
	s_movk_i32 s16, 0xb80
	v_mul_hi_i32 v24, v59, s18
	v_cmp_gt_i32_e64 s[16:17], s16, v164
	v_add_u32_e32 v60, v24, v59
	s_and_saveexec_b64 s[20:21], s[16:17]
	s_cbranch_execz .LBB0_139
	v_lshrrev_b32_e32 v24, 31, v60
	v_ashrrev_i32_e32 v25, 10, v60
	v_add_u32_e32 v26, v25, v24
	v_mul_i32_i24_e32 v24, 0x5e0, v26
	v_sub_u32_e32 v28, v59, v24
	v_ashrrev_i32_e32 v24, 5, v28
	v_sub_u32_e32 v29, 15, v24
	v_min_i32_e32 v24, s35, v29
	v_sub_u32_e32 v24, s34, v24
	s_movk_i32 s18, 0x3000
	v_mul_lo_u32 v24, v24, s18
	v_ashrrev_i32_e32 v25, 31, v24
	v_lshlrev_b32_e32 v26, 8, v26
	v_lshl_add_u64 v[24:25], v[24:25], 1, s[74:75]
	v_ashrrev_i32_e32 v27, 31, v26
	v_lshl_add_u64 v[24:25], v[26:27], 1, v[24:25]
	v_lshlrev_b32_e32 v26, 4, v28
	v_and_b32_e32 v162, 0x1f0, v26
	v_lshl_add_u64 v[24:25], v[24:25], 0, v[162:163]
	global_load_dwordx4 v[24:27], v[24:25], off
	v_cmp_ge_i32_e64 s[18:19], s35, v29
	s_nop 1
	v_cndmask_b32_e64 v106, 0, 1, s[18:19]
.LBB0_139:
	s_or_b64 exec, exec, s[20:21]
	v_add_u32_e32 v61, 0xe00, v164
	s_mov_b32 s20, 0xae4c415d
	s_movk_i32 s18, 0x980
	v_mul_hi_i32 v28, v61, s20
	v_cmp_gt_i32_e64 s[18:19], s18, v164
	v_add_u32_e32 v62, v28, v61
	s_and_saveexec_b64 s[22:23], s[18:19]
	s_cbranch_execz .LBB0_141
	v_lshrrev_b32_e32 v28, 31, v62
	v_ashrrev_i32_e32 v29, 10, v62
	v_add_u32_e32 v30, v29, v28
	v_mul_i32_i24_e32 v28, 0x5e0, v30
	v_sub_u32_e32 v32, v61, v28
	v_ashrrev_i32_e32 v28, 5, v32
	v_sub_u32_e32 v33, 15, v28
	v_min_i32_e32 v28, s35, v33
	v_sub_u32_e32 v28, s34, v28
	s_movk_i32 s20, 0x3000
	v_mul_lo_u32 v28, v28, s20
	v_ashrrev_i32_e32 v29, 31, v28
	v_lshlrev_b32_e32 v30, 8, v30
	v_lshl_add_u64 v[28:29], v[28:29], 1, s[74:75]
	v_ashrrev_i32_e32 v31, 31, v30
	v_lshl_add_u64 v[28:29], v[30:31], 1, v[28:29]
	v_lshlrev_b32_e32 v30, 4, v32
	v_and_b32_e32 v162, 0x1f0, v30
	v_lshl_add_u64 v[28:29], v[28:29], 0, v[162:163]
	global_load_dwordx4 v[28:31], v[28:29], off
	v_cmp_ge_i32_e64 s[20:21], s35, v33
	s_nop 1
	v_cndmask_b32_e64 v107, 0, 1, s[20:21]
.LBB0_141:
	s_or_b64 exec, exec, s[22:23]
	v_add_u32_e32 v63, 0x1000, v164
	s_mov_b32 s22, 0xae4c415d
	s_movk_i32 s20, 0x780
	v_mul_hi_i32 v32, v63, s22
	v_cmp_gt_i32_e64 s[20:21], s20, v164
	v_add_u32_e32 v64, v32, v63
	s_and_saveexec_b64 s[24:25], s[20:21]
	s_cbranch_execz .LBB0_143
	v_lshrrev_b32_e32 v32, 31, v64
	v_ashrrev_i32_e32 v33, 10, v64
	v_add_u32_e32 v34, v33, v32
	v_mul_i32_i24_e32 v32, 0x5e0, v34
	v_sub_u32_e32 v36, v63, v32
	v_ashrrev_i32_e32 v32, 5, v36
	v_sub_u32_e32 v37, 15, v32
	v_min_i32_e32 v32, s35, v37
	v_sub_u32_e32 v32, s34, v32
	s_movk_i32 s22, 0x3000
	v_mul_lo_u32 v32, v32, s22
	v_ashrrev_i32_e32 v33, 31, v32
	v_lshlrev_b32_e32 v34, 8, v34
	v_lshl_add_u64 v[32:33], v[32:33], 1, s[74:75]
	v_ashrrev_i32_e32 v35, 31, v34
	v_lshl_add_u64 v[32:33], v[34:35], 1, v[32:33]
	v_lshlrev_b32_e32 v34, 4, v36
	v_and_b32_e32 v162, 0x1f0, v34
	v_lshl_add_u64 v[32:33], v[32:33], 0, v[162:163]
	global_load_dwordx4 v[32:35], v[32:33], off
	v_cmp_ge_i32_e64 s[22:23], s35, v37
	s_nop 1
	v_cndmask_b32_e64 v108, 0, 1, s[22:23]
.LBB0_143:
	s_or_b64 exec, exec, s[24:25]
	v_add_u32_e32 v65, 0x1200, v164
	s_mov_b32 s24, 0xae4c415d
	s_movk_i32 s22, 0x580
	v_mul_hi_i32 v36, v65, s24
	v_cmp_gt_i32_e64 s[22:23], s22, v164
	v_add_u32_e32 v66, v36, v65
	s_and_saveexec_b64 s[26:27], s[22:23]
	s_cbranch_execz .LBB0_145
	v_lshrrev_b32_e32 v36, 31, v66
	v_ashrrev_i32_e32 v37, 10, v66
	v_add_u32_e32 v38, v37, v36
	v_mul_i32_i24_e32 v36, 0x5e0, v38
	v_sub_u32_e32 v40, v65, v36
	v_ashrrev_i32_e32 v36, 5, v40
	v_sub_u32_e32 v41, 15, v36
	v_min_i32_e32 v36, s35, v41
	v_sub_u32_e32 v36, s34, v36
	s_movk_i32 s24, 0x3000
	v_mul_lo_u32 v36, v36, s24
	v_ashrrev_i32_e32 v37, 31, v36
	v_lshlrev_b32_e32 v38, 8, v38
	v_lshl_add_u64 v[36:37], v[36:37], 1, s[74:75]
	v_ashrrev_i32_e32 v39, 31, v38
	v_lshl_add_u64 v[36:37], v[38:39], 1, v[36:37]
	v_lshlrev_b32_e32 v38, 4, v40
	v_and_b32_e32 v162, 0x1f0, v38
	v_lshl_add_u64 v[36:37], v[36:37], 0, v[162:163]
	global_load_dwordx4 v[36:39], v[36:37], off
	v_cmp_ge_i32_e64 s[24:25], s35, v41
	s_nop 1
	v_cndmask_b32_e64 v109, 0, 1, s[24:25]
; __device__ __forceinline__ void pool_block_item(const Params& p, int layer, int tt, const int tidx) {
;     ...
;     u32x4 xv[12];
; #pragma unroll
;     for (int i = 0; i < 12; ++i) {
;       int c = i * NTHR + tidx;
;       if (c < 4 * PROWS * 32) {
;         int g = c / (PROWS * 32), rem = c % (PROWS * 32), r = rem >> 5, c16 = rem & 31;
;         int back = 15 - r;
;         const bool pre = back > pos0;
;         if (pre) back = pos0;
;         xv[i] = *reinterpret_cast<const u32x4*>(proj + (size_t)(t0 - back) * DIN + OFF_PX + g * 256 + c16 * 8);
;         if (pre) xv[i] = u32x4{0u, 0u, 0u, 0u};
;       }
;     }
.LBB0_145:
	s_or_b64 exec, exec, s[26:27]
	v_add_u32_e32 v67, 0x1400, v164
	s_mov_b32 s26, 0xae4c415d
	s_movk_i32 s24, 0x380
	v_mul_hi_i32 v40, v67, s26
	v_cmp_gt_i32_e64 s[24:25], s24, v164
	v_add_u32_e32 v68, v40, v67
	s_and_saveexec_b64 s[28:29], s[24:25]
	s_cbranch_execz .LBB0_147
	v_lshrrev_b32_e32 v40, 31, v68
	v_ashrrev_i32_e32 v41, 10, v68
	v_add_u32_e32 v42, v41, v40
	v_mul_i32_i24_e32 v40, 0x5e0, v42
	v_sub_u32_e32 v44, v67, v40
	v_ashrrev_i32_e32 v40, 5, v44
	v_sub_u32_e32 v45, 15, v40
	v_min_i32_e32 v40, s35, v45
	v_sub_u32_e32 v40, s34, v40
	s_movk_i32 s26, 0x3000
	v_mul_lo_u32 v40, v40, s26
	v_ashrrev_i32_e32 v41, 31, v40
	v_lshlrev_b32_e32 v42, 8, v42
	v_lshl_add_u64 v[40:41], v[40:41], 1, s[74:75]
	v_ashrrev_i32_e32 v43, 31, v42
	v_lshl_add_u64 v[40:41], v[42:43], 1, v[40:41]
	v_lshlrev_b32_e32 v42, 4, v44
	v_and_b32_e32 v162, 0x1f0, v42
	v_lshl_add_u64 v[40:41], v[40:41], 0, v[162:163]
	global_load_dwordx4 v[40:43], v[40:41], off
	v_cmp_ge_i32_e64 s[26:27], s35, v45
	s_nop 1
	v_cndmask_b32_e64 v110, 0, 1, s[26:27]
.LBB0_147:
	s_or_b64 exec, exec, s[28:29]
	v_add_u32_e32 v69, 0x1600, v164
	s_mov_b32 s28, 0xae4c415d
	s_movk_i32 s26, 0x180
	v_mul_hi_i32 v44, v69, s28
	v_cmp_gt_i32_e64 s[26:27], s26, v164
	v_add_u32_e32 v70, v44, v69
	s_and_saveexec_b64 s[30:31], s[26:27]
	s_cbranch_execz .LBB0_149
	v_lshrrev_b32_e32 v44, 31, v70
	v_ashrrev_i32_e32 v45, 10, v70
	v_add_u32_e32 v46, v45, v44
	v_mul_i32_i24_e32 v44, 0x5e0, v46
	v_sub_u32_e32 v71, v69, v44
	v_ashrrev_i32_e32 v44, 5, v71
	v_sub_u32_e32 v72, 15, v44
	v_min_i32_e32 v44, s35, v72
	v_sub_u32_e32 v44, s34, v44
	s_movk_i32 s28, 0x3000
	v_mul_lo_u32 v44, v44, s28
	v_ashrrev_i32_e32 v45, 31, v44
	v_lshlrev_b32_e32 v46, 8, v46
	v_lshl_add_u64 v[44:45], v[44:45], 1, s[74:75]
	v_ashrrev_i32_e32 v47, 31, v46
	v_lshl_add_u64 v[44:45], v[46:47], 1, v[44:45]
	v_lshlrev_b32_e32 v46, 4, v71
	v_and_b32_e32 v162, 0x1f0, v46
	v_lshl_add_u64 v[44:45], v[44:45], 0, v[162:163]
	global_load_dwordx4 v[44:47], v[44:45], off
	v_cmp_ge_i32_e64 s[28:29], s35, v72
	s_nop 1
	v_cndmask_b32_e64 v111, 0, 1, s[28:29]
.LBB0_149:
	s_or_b64 exec, exec, s[30:31]
	s_waitcnt vmcnt(0)
	v_cmp_ne_u32_e64 s[28:29], 0, v100
	s_nop 1
	v_cndmask_b32_e64 v0, 0, v0, s[28:29]
	v_cndmask_b32_e64 v1, 0, v1, s[28:29]
	v_cndmask_b32_e64 v2, 0, v2, s[28:29]
	v_cndmask_b32_e64 v3, 0, v3, s[28:29]
	v_cmp_ne_u32_e64 s[28:29], 0, v101
	s_nop 1
	v_cndmask_b32_e64 v4, 0, v4, s[28:29]
	v_cndmask_b32_e64 v5, 0, v5, s[28:29]
	v_cndmask_b32_e64 v6, 0, v6, s[28:29]
	v_cndmask_b32_e64 v7, 0, v7, s[28:29]
	v_cmp_ne_u32_e64 s[28:29], 0, v102
	s_nop 1
	v_cndmask_b32_e64 v8, 0, v8, s[28:29]
	v_cndmask_b32_e64 v9, 0, v9, s[28:29]
	v_cndmask_b32_e64 v10, 0, v10, s[28:29]
	v_cndmask_b32_e64 v11, 0, v11, s[28:29]
	v_cmp_ne_u32_e64 s[28:29], 0, v103
	s_nop 1
	v_cndmask_b32_e64 v12, 0, v12, s[28:29]
	v_cndmask_b32_e64 v13, 0, v13, s[28:29]
	v_cndmask_b32_e64 v14, 0, v14, s[28:29]
	v_cndmask_b32_e64 v15, 0, v15, s[28:29]
	v_cmp_ne_u32_e64 s[28:29], 0, v104
	s_nop 1
	v_cndmask_b32_e64 v16, 0, v16, s[28:29]
	v_cndmask_b32_e64 v17, 0, v17, s[28:29]
	v_cndmask_b32_e64 v18, 0, v18, s[28:29]
	v_cndmask_b32_e64 v19, 0, v19, s[28:29]
	v_cmp_ne_u32_e64 s[28:29], 0, v105
	s_nop 1
	v_cndmask_b32_e64 v20, 0, v20, s[28:29]
	v_cndmask_b32_e64 v21, 0, v21, s[28:29]
	v_cndmask_b32_e64 v22, 0, v22, s[28:29]
	v_cndmask_b32_e64 v23, 0, v23, s[28:29]
	v_cmp_ne_u32_e64 s[28:29], 0, v106
	s_nop 1
	v_cndmask_b32_e64 v24, 0, v24, s[28:29]
	v_cndmask_b32_e64 v25, 0, v25, s[28:29]
	v_cndmask_b32_e64 v26, 0, v26, s[28:29]
	v_cndmask_b32_e64 v27, 0, v27, s[28:29]
	v_cmp_ne_u32_e64 s[28:29], 0, v107
	s_nop 1
	v_cndmask_b32_e64 v28, 0, v28, s[28:29]
	v_cndmask_b32_e64 v29, 0, v29, s[28:29]
	v_cndmask_b32_e64 v30, 0, v30, s[28:29]
	v_cndmask_b32_e64 v31, 0, v31, s[28:29]
	v_cmp_ne_u32_e64 s[28:29], 0, v108
	s_nop 1
	v_cndmask_b32_e64 v32, 0, v32, s[28:29]
	v_cndmask_b32_e64 v33, 0, v33, s[28:29]
	v_cndmask_b32_e64 v34, 0, v34, s[28:29]
	v_cndmask_b32_e64 v35, 0, v35, s[28:29]
	v_cmp_ne_u32_e64 s[28:29], 0, v109
	s_nop 1
	v_cndmask_b32_e64 v36, 0, v36, s[28:29]
	v_cndmask_b32_e64 v37, 0, v37, s[28:29]
	v_cndmask_b32_e64 v38, 0, v38, s[28:29]
	v_cndmask_b32_e64 v39, 0, v39, s[28:29]
	v_cmp_ne_u32_e64 s[28:29], 0, v110
	s_nop 1
	v_cndmask_b32_e64 v40, 0, v40, s[28:29]
	v_cndmask_b32_e64 v41, 0, v41, s[28:29]
	v_cndmask_b32_e64 v42, 0, v42, s[28:29]
	v_cndmask_b32_e64 v43, 0, v43, s[28:29]
	v_cmp_ne_u32_e64 s[28:29], 0, v111
	s_nop 1
	v_cndmask_b32_e64 v44, 0, v44, s[28:29]
	v_cndmask_b32_e64 v45, 0, v45, s[28:29]
	v_cndmask_b32_e64 v46, 0, v46, s[28:29]
	v_cndmask_b32_e64 v47, 0, v47, s[28:29]
	s_and_saveexec_b64 s[28:29], vcc
	s_cbranch_execnz .LBB0_167
	s_or_b64 exec, exec, s[28:29]
	s_and_saveexec_b64 s[28:29], s[6:7]
	s_cbranch_execnz .LBB0_168
